# code placement: .p2align 6 on the heads of the seven GEMM K-loops, the attention tile loop and the retention chunk loop
# baseline (speedup 1.0000x reference)
.LBB0_114:
	s_ashr_i32 s43, s42, 31
	s_lshl_b64 s[44:45], s[42:43], 19
	s_add_u32 s44, s55, s44
	s_addc_u32 s45, s56, s45
	s_and_b64 s[46:47], s[2:3], exec
	s_cselect_b32 s7, s45, s5
	s_cselect_b32 s43, s44, s4
	s_ashr_i32 s41, s40, 31
	s_lshl_b64 s[46:47], s[40:41], 19
	s_add_u32 s46, s57, s46
	s_addc_u32 s47, s58, s47
	s_and_b64 s[50:51], s[2:3], exec
	s_cselect_b32 s41, s47, s1
	s_cselect_b32 s49, s46, s0
	s_add_i32 s52, s14, -2
	s_lshl_b32 s14, s14, 7
	s_add_u32 s53, s4, 0x100
	s_addc_u32 s80, s5, 0
	s_add_u32 s4, s4, 0x40080
	s_addc_u32 s5, s5, 0
	s_add_u32 s81, s0, 0x100
	v_lshl_add_u64 v[142:143], s[4:5], 0, v[130:131]
	v_lshl_add_u64 v[144:145], s[4:5], 0, v[134:135]
	s_addc_u32 s82, s1, 0
	s_mov_b64 s[0:1], 0x700
	.p2align	6

.LBB0_508:
	s_waitcnt lgkmcnt(0)
	s_barrier
	s_andn2_b64 vcc, exec, s[0:1]
	s_mov_b32 s0, 0
	s_cbranch_vccnz .LBB0_525
	v_add_u32_e32 v174, s64, v202
	s_mov_b32 s36, 3
	s_mov_b32 s37, 2
	s_mov_b32 s0, 1
	s_mov_b32 s64, 0
	s_mov_b32 s65, 0
	s_mov_b32 s1, 1
	s_mov_b32 s66, 0
	s_mov_b32 s67, 2
	.p2align	6

.LBB0_592:
	s_or_b64 exec, exec, s[70:71]
	s_mov_b64 s[70:71], 0x40000
	s_add_i32 s85, s85, -1
	v_lshl_add_u64 v[178:179], v[178:179], 0, s[70:71]
	s_mov_b64 s[70:71], 0x8000
	v_lshl_add_u64 v[180:181], v[180:181], 0, s[96:97]
	v_lshl_add_u64 v[182:183], v[182:183], 0, s[70:71]
	s_cmp_lg_u32 s85, 0
	v_lshl_add_u64 v[184:185], v[184:185], 0, s[96:97]
	s_waitcnt lgkmcnt(0)
	s_barrier
	s_cbranch_scc0 .LBB0_588
	.p2align	6

.LBB0_688:
	s_ashr_i32 s43, s42, 31
	s_lshl_b64 s[44:45], s[42:43], 19
	s_add_u32 s44, s39, s44
	s_addc_u32 s45, s52, s45
	s_and_b64 s[46:47], s[2:3], exec
	s_cselect_b32 s5, s45, s49
	s_cselect_b32 s43, s44, s48
	s_ashr_i32 s41, s40, 31
	s_lshl_b64 s[46:47], s[40:41], 19
	s_add_u32 s46, s53, s46
	s_addc_u32 s47, s54, s47
	s_and_b64 s[50:51], s[2:3], exec
	s_cselect_b32 s41, s47, s1
	s_cselect_b32 s79, s46, s0
	s_add_i32 s80, s10, -2
	s_lshl_b32 s10, s10, 7
	s_add_u32 s81, s48, 0x100
	s_addc_u32 s82, s49, 0
	s_add_u32 s48, s48, 0x40080
	s_addc_u32 s49, s49, 0
	s_add_u32 s83, s0, 0x100
	v_lshl_add_u64 v[130:131], s[48:49], 0, v[134:135]
	v_lshl_add_u64 v[132:133], s[48:49], 0, v[138:139]
	s_addc_u32 s84, s1, 0
	s_mov_b64 s[0:1], 0x700
	.p2align	6

.LBB0_770:
	s_ashr_i32 s27, s26, 31
	s_lshl_b64 s[28:29], s[26:27], 19
	s_add_u32 s28, s4, s28
	s_addc_u32 s29, s5, s29
	s_and_b64 s[30:31], s[2:3], exec
	s_cselect_b32 s27, s29, s1
	s_cselect_b32 s54, s28, s0
	s_ashr_i32 s25, s24, 31
	s_lshl_b64 s[30:31], s[24:25], 19
	s_add_u32 s30, s41, s30
	s_addc_u32 s31, s42, s31
	s_and_b64 s[38:39], s[2:3], exec
	s_cselect_b32 s25, s31, s37
	s_cselect_b32 s55, s30, s36
	s_add_u32 s0, s0, 0x40080
	s_addc_u32 s1, s1, 0
	s_add_u32 s56, s36, 0x100
	v_mov_b32_e32 v58, 0
	s_addc_u32 s57, s37, 0
	s_mov_b32 s58, -2
	v_mov_b32_e32 v59, v58
	v_mov_b32_e32 v60, v58
	v_mov_b32_e32 v61, v58
	v_mov_b32_e32 v62, v58
	v_mov_b32_e32 v63, v58
	v_mov_b32_e32 v64, v58
	v_mov_b32_e32 v65, v58
	v_mov_b32_e32 v42, v58
	v_mov_b32_e32 v43, v58
	v_mov_b32_e32 v44, v58
	v_mov_b32_e32 v45, v58
	v_mov_b32_e32 v46, v58
	v_mov_b32_e32 v47, v58
	v_mov_b32_e32 v48, v58
	v_mov_b32_e32 v49, v58
	v_mov_b32_e32 v26, v58
	v_mov_b32_e32 v27, v58
	v_mov_b32_e32 v28, v58
	v_mov_b32_e32 v29, v58
	v_mov_b32_e32 v30, v58
	v_mov_b32_e32 v31, v58
	v_mov_b32_e32 v32, v58
	v_mov_b32_e32 v33, v58
	v_mov_b32_e32 v10, v58
	v_mov_b32_e32 v11, v58
	v_mov_b32_e32 v12, v58
	v_mov_b32_e32 v13, v58
	v_mov_b32_e32 v14, v58
	v_mov_b32_e32 v15, v58
	v_mov_b32_e32 v16, v58
	v_mov_b32_e32 v17, v58
	v_mov_b32_e32 v50, v58
	v_mov_b32_e32 v51, v58
	v_mov_b32_e32 v52, v58
	v_mov_b32_e32 v53, v58
	v_mov_b32_e32 v54, v58
	v_mov_b32_e32 v55, v58
	v_mov_b32_e32 v56, v58
	v_mov_b32_e32 v57, v58
	v_mov_b32_e32 v34, v58
	v_mov_b32_e32 v35, v58
	v_mov_b32_e32 v36, v58
	v_mov_b32_e32 v37, v58
	v_mov_b32_e32 v38, v58
	v_mov_b32_e32 v39, v58
	v_mov_b32_e32 v40, v58
	v_mov_b32_e32 v41, v58
	v_mov_b32_e32 v18, v58
	v_mov_b32_e32 v19, v58
	v_mov_b32_e32 v20, v58
	v_mov_b32_e32 v21, v58
	v_mov_b32_e32 v22, v58
	v_mov_b32_e32 v23, v58
	v_mov_b32_e32 v24, v58
	v_mov_b32_e32 v25, v58
	v_mov_b32_e32 v2, v58
	v_mov_b32_e32 v3, v58
	v_mov_b32_e32 v4, v58
	v_mov_b32_e32 v5, v58
	v_mov_b32_e32 v6, v58
	v_mov_b32_e32 v7, v58
	v_mov_b32_e32 v8, v58
	v_mov_b32_e32 v9, v58
	v_mov_b32_e32 v66, v58
	v_mov_b32_e32 v67, v58
	v_mov_b32_e32 v68, v58
	v_mov_b32_e32 v69, v58
	v_mov_b32_e32 v70, v58
	v_mov_b32_e32 v71, v58
	v_mov_b32_e32 v72, v58
	v_mov_b32_e32 v73, v58
	v_mov_b32_e32 v82, v58
	v_mov_b32_e32 v83, v58
	v_mov_b32_e32 v84, v58
	v_mov_b32_e32 v85, v58
	v_mov_b32_e32 v86, v58
	v_mov_b32_e32 v87, v58
	v_mov_b32_e32 v88, v58
	v_mov_b32_e32 v89, v58
	v_mov_b32_e32 v98, v58
	v_mov_b32_e32 v99, v58
	v_mov_b32_e32 v100, v58
	v_mov_b32_e32 v101, v58
	v_mov_b32_e32 v102, v58
	v_mov_b32_e32 v103, v58
	v_mov_b32_e32 v104, v58
	v_mov_b32_e32 v105, v58
	v_mov_b32_e32 v114, v58
	v_mov_b32_e32 v115, v58
	v_mov_b32_e32 v116, v58
	v_mov_b32_e32 v117, v58
	v_mov_b32_e32 v118, v58
	v_mov_b32_e32 v119, v58
	v_mov_b32_e32 v120, v58
	v_mov_b32_e32 v121, v58
	v_mov_b32_e32 v74, v58
	v_mov_b32_e32 v75, v58
	v_mov_b32_e32 v76, v58
	v_mov_b32_e32 v77, v58
	v_mov_b32_e32 v78, v58
	v_mov_b32_e32 v79, v58
	v_mov_b32_e32 v80, v58
	v_mov_b32_e32 v81, v58
	v_mov_b32_e32 v90, v58
	v_mov_b32_e32 v91, v58
	v_mov_b32_e32 v92, v58
	v_mov_b32_e32 v93, v58
	v_mov_b32_e32 v94, v58
	v_mov_b32_e32 v95, v58
	v_mov_b32_e32 v96, v58
	v_mov_b32_e32 v97, v58
	v_mov_b32_e32 v106, v58
	v_mov_b32_e32 v107, v58
	v_mov_b32_e32 v108, v58
	v_mov_b32_e32 v109, v58
	v_mov_b32_e32 v110, v58
	v_mov_b32_e32 v111, v58
	v_mov_b32_e32 v112, v58
	v_mov_b32_e32 v113, v58
	v_mov_b32_e32 v122, v58
	v_mov_b32_e32 v123, v58
	v_mov_b32_e32 v124, v58
	v_mov_b32_e32 v125, v58
	v_mov_b32_e32 v126, v58
	v_mov_b32_e32 v127, v58
	v_mov_b32_e32 v128, v58
	v_mov_b32_e32 v129, v58
	.p2align	6

.LBB0_795:
	s_ashr_i32 s21, s20, 31
	s_lshl_b64 s[22:23], s[20:21], 20
	s_add_u32 s22, s35, s22
	s_addc_u32 s23, s36, s23
	s_and_b64 s[24:25], s[2:3], exec
	s_cselect_b32 s21, s23, s1
	s_cselect_b32 s50, s22, s0
	s_ashr_i32 s19, s18, 31
	s_lshl_b64 s[24:25], s[18:19], 20
	s_add_u32 s24, s37, s24
	s_addc_u32 s25, s38, s25
	s_and_b64 s[30:31], s[2:3], exec
	s_cselect_b32 s19, s25, s29
	s_cselect_b32 s51, s24, s28
	s_add_u32 s0, s0, 0x80080
	s_addc_u32 s1, s1, 0
	s_add_u32 s52, s28, 0x100
	v_mov_b32_e32 v26, 0
	s_addc_u32 s53, s29, 0
	s_mov_b32 s54, -2
	v_mov_b32_e32 v27, v26
	v_mov_b32_e32 v28, v26
	v_mov_b32_e32 v29, v26
	v_mov_b32_e32 v30, v26
	v_mov_b32_e32 v31, v26
	v_mov_b32_e32 v32, v26
	v_mov_b32_e32 v33, v26
	v_mov_b32_e32 v10, v26
	v_mov_b32_e32 v11, v26
	v_mov_b32_e32 v12, v26
	v_mov_b32_e32 v13, v26
	v_mov_b32_e32 v14, v26
	v_mov_b32_e32 v15, v26
	v_mov_b32_e32 v16, v26
	v_mov_b32_e32 v17, v26
	v_mov_b32_e32 v34, v26
	v_mov_b32_e32 v35, v26
	v_mov_b32_e32 v36, v26
	v_mov_b32_e32 v37, v26
	v_mov_b32_e32 v38, v26
	v_mov_b32_e32 v39, v26
	v_mov_b32_e32 v40, v26
	v_mov_b32_e32 v41, v26
	v_mov_b32_e32 v50, v26
	v_mov_b32_e32 v51, v26
	v_mov_b32_e32 v52, v26
	v_mov_b32_e32 v53, v26
	v_mov_b32_e32 v54, v26
	v_mov_b32_e32 v55, v26
	v_mov_b32_e32 v56, v26
	v_mov_b32_e32 v57, v26
	v_mov_b32_e32 v18, v26
	v_mov_b32_e32 v19, v26
	v_mov_b32_e32 v20, v26
	v_mov_b32_e32 v21, v26
	v_mov_b32_e32 v22, v26
	v_mov_b32_e32 v23, v26
	v_mov_b32_e32 v24, v26
	v_mov_b32_e32 v25, v26
	v_mov_b32_e32 v2, v26
	v_mov_b32_e32 v3, v26
	v_mov_b32_e32 v4, v26
	v_mov_b32_e32 v5, v26
	v_mov_b32_e32 v6, v26
	v_mov_b32_e32 v7, v26
	v_mov_b32_e32 v8, v26
	v_mov_b32_e32 v9, v26
	v_mov_b32_e32 v42, v26
	v_mov_b32_e32 v43, v26
	v_mov_b32_e32 v44, v26
	v_mov_b32_e32 v45, v26
	v_mov_b32_e32 v46, v26
	v_mov_b32_e32 v47, v26
	v_mov_b32_e32 v48, v26
	v_mov_b32_e32 v49, v26
	v_mov_b32_e32 v58, v26
	v_mov_b32_e32 v59, v26
	v_mov_b32_e32 v60, v26
	v_mov_b32_e32 v61, v26
	v_mov_b32_e32 v62, v26
	v_mov_b32_e32 v63, v26
	v_mov_b32_e32 v64, v26
	v_mov_b32_e32 v65, v26
	v_mov_b32_e32 v66, v26
	v_mov_b32_e32 v67, v26
	v_mov_b32_e32 v68, v26
	v_mov_b32_e32 v69, v26
	v_mov_b32_e32 v70, v26
	v_mov_b32_e32 v71, v26
	v_mov_b32_e32 v72, v26
	v_mov_b32_e32 v73, v26
	v_mov_b32_e32 v82, v26
	v_mov_b32_e32 v83, v26
	v_mov_b32_e32 v84, v26
	v_mov_b32_e32 v85, v26
	v_mov_b32_e32 v86, v26
	v_mov_b32_e32 v87, v26
	v_mov_b32_e32 v88, v26
	v_mov_b32_e32 v89, v26
	v_mov_b32_e32 v98, v26
	v_mov_b32_e32 v99, v26
	v_mov_b32_e32 v100, v26
	v_mov_b32_e32 v101, v26
	v_mov_b32_e32 v102, v26
	v_mov_b32_e32 v103, v26
	v_mov_b32_e32 v104, v26
	v_mov_b32_e32 v105, v26
	v_mov_b32_e32 v114, v26
	v_mov_b32_e32 v115, v26
	v_mov_b32_e32 v116, v26
	v_mov_b32_e32 v117, v26
	v_mov_b32_e32 v118, v26
	v_mov_b32_e32 v119, v26
	v_mov_b32_e32 v120, v26
	v_mov_b32_e32 v121, v26
	v_mov_b32_e32 v74, v26
	v_mov_b32_e32 v75, v26
	v_mov_b32_e32 v76, v26
	v_mov_b32_e32 v77, v26
	v_mov_b32_e32 v78, v26
	v_mov_b32_e32 v79, v26
	v_mov_b32_e32 v80, v26
	v_mov_b32_e32 v81, v26
	v_mov_b32_e32 v90, v26
	v_mov_b32_e32 v91, v26
	v_mov_b32_e32 v92, v26
	v_mov_b32_e32 v93, v26
	v_mov_b32_e32 v94, v26
	v_mov_b32_e32 v95, v26
	v_mov_b32_e32 v96, v26
	v_mov_b32_e32 v97, v26
	v_mov_b32_e32 v106, v26
	v_mov_b32_e32 v107, v26
	v_mov_b32_e32 v108, v26
	v_mov_b32_e32 v109, v26
	v_mov_b32_e32 v110, v26
	v_mov_b32_e32 v111, v26
	v_mov_b32_e32 v112, v26
	v_mov_b32_e32 v113, v26
	v_mov_b32_e32 v122, v26
	v_mov_b32_e32 v123, v26
	v_mov_b32_e32 v124, v26
	v_mov_b32_e32 v125, v26
	v_mov_b32_e32 v126, v26
	v_mov_b32_e32 v127, v26
	v_mov_b32_e32 v128, v26
	v_mov_b32_e32 v129, v26
	.p2align	6

.LBB0_874:
	s_ashr_i32 s29, s28, 31
	s_lshl_b64 s[30:31], s[28:29], 19
	s_add_u32 s30, s42, s30
	s_addc_u32 s31, s43, s31
	s_and_b64 s[34:35], s[4:5], exec
	s_cselect_b32 s29, s31, s1
	s_cselect_b32 s37, s30, s0
	s_ashr_i32 s27, s26, 31
	s_lshl_b64 s[34:35], s[26:27], 19
	s_add_u32 s34, s44, s34
	s_addc_u32 s35, s45, s35
	s_and_b64 s[40:41], s[4:5], exec
	s_cselect_b32 s27, s35, s39
	s_cselect_b32 s59, s34, s38
	s_add_u32 s0, s0, 0x40080
	s_addc_u32 s1, s1, 0
	s_add_u32 s60, s38, 0x100
	v_mov_b32_e32 v2, 0
	s_addc_u32 s61, s39, 0
	s_mov_b32 s62, -2
	v_mov_b32_e32 v3, v2
	v_mov_b32_e32 v4, v2
	v_mov_b32_e32 v5, v2
	v_mov_b32_e32 v6, v2
	v_mov_b32_e32 v7, v2
	v_mov_b32_e32 v8, v2
	v_mov_b32_e32 v9, v2
	v_mov_b32_e32 v18, v2
	v_mov_b32_e32 v19, v2
	v_mov_b32_e32 v20, v2
	v_mov_b32_e32 v21, v2
	v_mov_b32_e32 v22, v2
	v_mov_b32_e32 v23, v2
	v_mov_b32_e32 v24, v2
	v_mov_b32_e32 v25, v2
	v_mov_b32_e32 v34, v2
	v_mov_b32_e32 v35, v2
	v_mov_b32_e32 v36, v2
	v_mov_b32_e32 v37, v2
	v_mov_b32_e32 v38, v2
	v_mov_b32_e32 v39, v2
	v_mov_b32_e32 v40, v2
	v_mov_b32_e32 v41, v2
	v_mov_b32_e32 v46, v2
	v_mov_b32_e32 v47, v2
	v_mov_b32_e32 v48, v2
	v_mov_b32_e32 v49, v2
	v_mov_b32_e32 v54, v2
	v_mov_b32_e32 v55, v2
	v_mov_b32_e32 v56, v2
	v_mov_b32_e32 v57, v2
	v_mov_b32_e32 v10, v2
	v_mov_b32_e32 v11, v2
	v_mov_b32_e32 v12, v2
	v_mov_b32_e32 v13, v2
	v_mov_b32_e32 v14, v2
	v_mov_b32_e32 v15, v2
	v_mov_b32_e32 v16, v2
	v_mov_b32_e32 v17, v2
	v_mov_b32_e32 v26, v2
	v_mov_b32_e32 v27, v2
	v_mov_b32_e32 v28, v2
	v_mov_b32_e32 v29, v2
	v_mov_b32_e32 v30, v2
	v_mov_b32_e32 v31, v2
	v_mov_b32_e32 v32, v2
	v_mov_b32_e32 v33, v2
	v_mov_b32_e32 v42, v2
	v_mov_b32_e32 v43, v2
	v_mov_b32_e32 v44, v2
	v_mov_b32_e32 v45, v2
	v_mov_b32_e32 v50, v2
	v_mov_b32_e32 v51, v2
	v_mov_b32_e32 v52, v2
	v_mov_b32_e32 v53, v2
	v_mov_b32_e32 v58, v2
	v_mov_b32_e32 v59, v2
	v_mov_b32_e32 v60, v2
	v_mov_b32_e32 v61, v2
	v_mov_b32_e32 v62, v2
	v_mov_b32_e32 v63, v2
	v_mov_b32_e32 v64, v2
	v_mov_b32_e32 v65, v2
	v_mov_b32_e32 v66, v2
	v_mov_b32_e32 v67, v2
	v_mov_b32_e32 v68, v2
	v_mov_b32_e32 v69, v2
	v_mov_b32_e32 v70, v2
	v_mov_b32_e32 v71, v2
	v_mov_b32_e32 v72, v2
	v_mov_b32_e32 v73, v2
	v_mov_b32_e32 v78, v2
	v_mov_b32_e32 v79, v2
	v_mov_b32_e32 v80, v2
	v_mov_b32_e32 v81, v2
	v_mov_b32_e32 v86, v2
	v_mov_b32_e32 v87, v2
	v_mov_b32_e32 v88, v2
	v_mov_b32_e32 v89, v2
	v_mov_b32_e32 v98, v2
	v_mov_b32_e32 v99, v2
	v_mov_b32_e32 v100, v2
	v_mov_b32_e32 v101, v2
	v_mov_b32_e32 v102, v2
	v_mov_b32_e32 v103, v2
	v_mov_b32_e32 v104, v2
	v_mov_b32_e32 v105, v2
	v_mov_b32_e32 v106, v2
	v_mov_b32_e32 v107, v2
	v_mov_b32_e32 v108, v2
	v_mov_b32_e32 v109, v2
	v_mov_b32_e32 v114, v2
	v_mov_b32_e32 v115, v2
	v_mov_b32_e32 v116, v2
	v_mov_b32_e32 v117, v2
	v_mov_b32_e32 v74, v2
	v_mov_b32_e32 v75, v2
	v_mov_b32_e32 v76, v2
	v_mov_b32_e32 v77, v2
	v_mov_b32_e32 v82, v2
	v_mov_b32_e32 v83, v2
	v_mov_b32_e32 v84, v2
	v_mov_b32_e32 v85, v2
	v_mov_b32_e32 v90, v2
	v_mov_b32_e32 v91, v2
	v_mov_b32_e32 v92, v2
	v_mov_b32_e32 v93, v2
	v_mov_b32_e32 v94, v2
	v_mov_b32_e32 v95, v2
	v_mov_b32_e32 v96, v2
	v_mov_b32_e32 v97, v2
	v_mov_b32_e32 v110, v2
	v_mov_b32_e32 v111, v2
	v_mov_b32_e32 v112, v2
	v_mov_b32_e32 v113, v2
	v_mov_b32_e32 v118, v2
	v_mov_b32_e32 v119, v2
	v_mov_b32_e32 v120, v2
	v_mov_b32_e32 v121, v2
	v_mov_b32_e32 v122, v2
	v_mov_b32_e32 v123, v2
	v_mov_b32_e32 v124, v2
	v_mov_b32_e32 v125, v2
	v_mov_b32_e32 v126, v2
	v_mov_b32_e32 v127, v2
	v_mov_b32_e32 v128, v2
	v_mov_b32_e32 v129, v2
	s_waitcnt vmcnt(0)
	.p2align	6

.LBB0_970:
	s_ashr_i32 s37, s36, 31
	s_lshl_b64 s[38:39], s[36:37], 19
	s_add_u32 s38, s31, s38
	s_addc_u32 s39, s42, s39
	s_and_b64 s[40:41], s[2:3], exec
	s_cselect_b32 s37, s39, s7
	s_cselect_b32 s61, s38, s6
	s_ashr_i32 s35, s34, 31
	s_lshl_b64 s[40:41], s[34:35], 19
	s_add_u32 s40, s43, s40
	s_addc_u32 s41, s44, s41
	s_and_b64 s[62:63], s[2:3], exec
	s_cselect_b32 s35, s41, s1
	s_cselect_b32 s62, s40, s0
	s_add_i32 s63, s8, -2
	s_lshl_b32 s12, s8, 7
	s_add_u32 s64, s6, 0x100
	s_addc_u32 s65, s7, 0
	s_add_u32 s6, s6, 0x40080
	s_addc_u32 s7, s7, 0
	s_add_u32 s66, s0, 0x100
	v_lshl_add_u64 v[142:143], s[6:7], 0, v[130:131]
	v_lshl_add_u64 v[144:145], s[6:7], 0, v[134:135]
	s_addc_u32 s67, s1, 0
	s_mov_b64 s[0:1], 0x700
	.p2align	6

.LBB0_1050:
	s_ashr_i32 s47, s46, 31
	s_lshl_b64 s[48:49], s[46:47], 21
	s_add_u32 s48, s60, s48
	s_addc_u32 s49, s61, s49
	s_and_b64 s[50:51], s[0:1], exec
	s_cselect_b32 s5, s49, s3
	s_cselect_b32 s47, s48, s2
	s_ashr_i32 s45, s44, 31
	s_lshl_b64 s[50:51], s[44:45], 21
	s_add_u32 s50, s62, s50
	s_addc_u32 s51, s63, s51
	s_and_b64 s[54:55], s[0:1], exec
	s_cselect_b32 s45, s51, s7
	s_cselect_b32 s53, s50, s6
	s_add_u32 s2, s2, 0x100080
	s_addc_u32 s3, s3, 0
	s_add_u32 s56, s6, 0x100
	v_mov_b32_e32 v0, 0
	s_addc_u32 s57, s7, 0
	s_mov_b32 s58, -2
	v_mov_b32_e32 v1, v0
	v_mov_b32_e32 v2, v0
	v_mov_b32_e32 v3, v0
	v_mov_b32_e32 v4, v0
	v_mov_b32_e32 v5, v0
	v_mov_b32_e32 v6, v0
	v_mov_b32_e32 v7, v0
	v_mov_b32_e32 v16, v0
	v_mov_b32_e32 v17, v0
	v_mov_b32_e32 v18, v0
	v_mov_b32_e32 v19, v0
	v_mov_b32_e32 v20, v0
	v_mov_b32_e32 v21, v0
	v_mov_b32_e32 v22, v0
	v_mov_b32_e32 v23, v0
	v_mov_b32_e32 v32, v0
	v_mov_b32_e32 v33, v0
	v_mov_b32_e32 v34, v0
	v_mov_b32_e32 v35, v0
	v_mov_b32_e32 v36, v0
	v_mov_b32_e32 v37, v0
	v_mov_b32_e32 v38, v0
	v_mov_b32_e32 v39, v0
	v_mov_b32_e32 v48, v0
	v_mov_b32_e32 v49, v0
	v_mov_b32_e32 v50, v0
	v_mov_b32_e32 v51, v0
	v_mov_b32_e32 v52, v0
	v_mov_b32_e32 v53, v0
	v_mov_b32_e32 v54, v0
	v_mov_b32_e32 v55, v0
	v_mov_b32_e32 v8, v0
	v_mov_b32_e32 v9, v0
	v_mov_b32_e32 v10, v0
	v_mov_b32_e32 v11, v0
	v_mov_b32_e32 v12, v0
	v_mov_b32_e32 v13, v0
	v_mov_b32_e32 v14, v0
	v_mov_b32_e32 v15, v0
	v_mov_b32_e32 v24, v0
	v_mov_b32_e32 v25, v0
	v_mov_b32_e32 v26, v0
	v_mov_b32_e32 v27, v0
	v_mov_b32_e32 v28, v0
	v_mov_b32_e32 v29, v0
	v_mov_b32_e32 v30, v0
	v_mov_b32_e32 v31, v0
	v_mov_b32_e32 v40, v0
	v_mov_b32_e32 v41, v0
	v_mov_b32_e32 v42, v0
	v_mov_b32_e32 v43, v0
	v_mov_b32_e32 v44, v0
	v_mov_b32_e32 v45, v0
	v_mov_b32_e32 v46, v0
	v_mov_b32_e32 v47, v0
	v_mov_b32_e32 v56, v0
	v_mov_b32_e32 v57, v0
	v_mov_b32_e32 v58, v0
	v_mov_b32_e32 v59, v0
	v_mov_b32_e32 v60, v0
	v_mov_b32_e32 v61, v0
	v_mov_b32_e32 v62, v0
	v_mov_b32_e32 v63, v0
	v_mov_b32_e32 v64, v0
	v_mov_b32_e32 v65, v0
	v_mov_b32_e32 v66, v0
	v_mov_b32_e32 v67, v0
	v_mov_b32_e32 v68, v0
	v_mov_b32_e32 v69, v0
	v_mov_b32_e32 v70, v0
	v_mov_b32_e32 v71, v0
	v_mov_b32_e32 v80, v0
	v_mov_b32_e32 v81, v0
	v_mov_b32_e32 v82, v0
	v_mov_b32_e32 v83, v0
	v_mov_b32_e32 v84, v0
	v_mov_b32_e32 v85, v0
	v_mov_b32_e32 v86, v0
	v_mov_b32_e32 v87, v0
	v_mov_b32_e32 v96, v0
	v_mov_b32_e32 v97, v0
	v_mov_b32_e32 v98, v0
	v_mov_b32_e32 v99, v0
	v_mov_b32_e32 v100, v0
	v_mov_b32_e32 v101, v0
	v_mov_b32_e32 v102, v0
	v_mov_b32_e32 v103, v0
	v_mov_b32_e32 v112, v0
	v_mov_b32_e32 v113, v0
	v_mov_b32_e32 v114, v0
	v_mov_b32_e32 v115, v0
	v_mov_b32_e32 v116, v0
	v_mov_b32_e32 v117, v0
	v_mov_b32_e32 v118, v0
	v_mov_b32_e32 v119, v0
	v_mov_b32_e32 v72, v0
	v_mov_b32_e32 v73, v0
	v_mov_b32_e32 v74, v0
	v_mov_b32_e32 v75, v0
	v_mov_b32_e32 v76, v0
	v_mov_b32_e32 v77, v0
	v_mov_b32_e32 v78, v0
	v_mov_b32_e32 v79, v0
	v_mov_b32_e32 v88, v0
	v_mov_b32_e32 v89, v0
	v_mov_b32_e32 v90, v0
	v_mov_b32_e32 v91, v0
	v_mov_b32_e32 v92, v0
	v_mov_b32_e32 v93, v0
	v_mov_b32_e32 v94, v0
	v_mov_b32_e32 v95, v0
	v_mov_b32_e32 v104, v0
	v_mov_b32_e32 v105, v0
	v_mov_b32_e32 v106, v0
	v_mov_b32_e32 v107, v0
	v_mov_b32_e32 v108, v0
	v_mov_b32_e32 v109, v0
	v_mov_b32_e32 v110, v0
	v_mov_b32_e32 v111, v0
	v_mov_b32_e32 v120, v0
	v_mov_b32_e32 v121, v0
	v_mov_b32_e32 v122, v0
	v_mov_b32_e32 v123, v0
	v_mov_b32_e32 v124, v0
	v_mov_b32_e32 v125, v0
	v_mov_b32_e32 v126, v0
	v_mov_b32_e32 v127, v0
	s_waitcnt vmcnt(0)
	.p2align	6
